# P2 prologue de-serialised: bias-table build straight-lined (both components' loads together) and issued with the ten parameter loads in one round trip; values formed behind the reductions with v_cndma
# baseline (speedup 1.0000x reference)
; __global__ void __launch_bounds__(NWAVES * 64, 2) mega_fwd(Args args) {
;     ...
;             float gq = fabsf(P.q_norm_g[F.lane]), gk = fabsf(P.k_norm_g[F.lane]), gb = fmaxf(fmaxf(fabsf(P.rel_bias[F.lane]), fabsf(P.rel_bias[64 + F.lane])), fmaxf(fabsf(P.rel_bias[128 + F.lane]), fabsf(P.rel_bias[192 + F.lane])));
;             gq = wave_max(gq); gk = wave_max(gk); gb = wave_max(gb);
;             const float bound = 64.f * C2 * gq * gk + 2.f * LOG2E * gb, shift = bound > 100.f ? bound : 0.f;
;             dattn::Outs OU{(const bf16*)(P.ws + WS_SG), (bf16*)(P.ws + WS_BR), P.subln_g, compute_lam(P, F.lane)};
;     ...
;             S.wcyc = 0ull;
;     ...
;             {
;                 if (F.tid == 0) *(float*)(al + dattn::L_MISC) = shift;
;                 for (int e = F.tid; e < 1024; e += NWAVES * 64) { const int c = e >> 9, jj = e & 511, d = jj - dattn::TAB_OFF;
;                     const int dd = d > 113 ? 113 : d;
;                     ((float*)(al + dattn::L_TAB))[e] = d < 0 ? -__builtin_inff() : (P.rel_bias[(t5_bucket(dd) * NH + cur.h) * 2 + c] - P.rel_bias[(31 * NH + cur.h) * 2 + c]) * LOG2E - shift; }
.LBB0_337:
	s_and_b64 vcc, exec, s[0:1]
	s_cbranch_vccnz .LBB0_465
	v_lshlrev_b32_e32 v1, 2, v162
	global_load_dword v2, v1, s[26:27]
	global_load_dword v3, v1, s[28:29]
	global_load_dword v4, v1, s[20:21] offset:768
	global_load_dword v5, v1, s[20:21] offset:512
	global_load_dword v6, v1, s[36:37]
	global_load_dword v7, v1, s[30:31]
	global_load_dword v8, v1, s[38:39]
	global_load_dword v9, v1, s[40:41]
	global_load_dword v10, v1, s[20:21] offset:256
	global_load_dword v11, v1, s[20:21]
	v_min_u32_e32 v20, 0x1a1, v0
	v_add_u32_e32 v20, 0xfffffed0, v20
	v_cmp_lt_u32_e32 vcc, 18, v20
	s_movk_i32 s22, 0x42
	s_lshl_b32 s2, s46, 1
	v_cndmask_b32_e64 v21, 16, 17, vcc
	v_cmp_lt_u32_e32 vcc, 20, v20
	s_movk_i32 s100, 0x12f
	v_cmp_lt_u32_e64 s[100:101], s100, v0
	v_cndmask_b32_e64 v22, 0, 1, vcc
	v_cmp_lt_u32_e32 vcc, 23, v20
	s_mov_b32 s26, 0x3fb8aa3b
	v_addc_co_u32_e32 v21, vcc, v21, v22, vcc
	v_cmp_lt_u32_e32 vcc, 26, v20
	s_nop 1
	v_cndmask_b32_e64 v22, 0, 1, vcc
	v_cmp_lt_u32_e32 vcc, 30, v20
	s_nop 1
	v_addc_co_u32_e32 v21, vcc, v21, v22, vcc
	v_cmp_lt_u32_e32 vcc, 34, v20
	s_nop 1
	v_cndmask_b32_e64 v22, 0, 1, vcc
	v_cmp_lt_u32_e32 vcc, 39, v20
	s_nop 1
	v_addc_co_u32_e32 v21, vcc, v21, v22, vcc
	v_cmp_lt_u32_e32 vcc, 45, v20
	s_nop 1
	v_cndmask_b32_e64 v22, 0, 1, vcc
	v_cmp_lt_u32_e32 vcc, 51, v20
	s_nop 1
	v_addc_co_u32_e32 v21, vcc, v21, v22, vcc
	v_cmp_lt_u32_e32 vcc, 58, v20
	s_nop 1
	v_cndmask_b32_e64 v22, 0, 1, vcc
	v_cmp_lt_u32_e32 vcc, s22, v20
	s_movk_i32 s22, 0x4c
	s_nop 0
	v_addc_co_u32_e32 v21, vcc, v21, v22, vcc
	v_cmp_lt_u32_e32 vcc, s22, v20
	s_movk_i32 s22, 0x56
	s_nop 0
	v_cndmask_b32_e64 v22, 0, 1, vcc
	v_cmp_lt_u32_e32 vcc, s22, v20
	s_movk_i32 s22, 0x62
	s_nop 0
	v_addc_co_u32_e32 v21, vcc, v21, v22, vcc
	v_cmp_lt_u32_e32 vcc, s22, v20
	s_movk_i32 s22, 0x70
	s_nop 0
	v_cndmask_b32_e64 v22, 0, 1, vcc
	v_cmp_lt_u32_e32 vcc, s22, v20
	s_nop 1
	v_addc_co_u32_e32 v21, vcc, v21, v22, vcc
	v_cmp_gt_u32_e32 vcc, 16, v20
	s_nop 1
	v_cndmask_b32_e32 v20, v21, v20, vcc
	v_lshl_or_b32 v20, v20, 3, s2
	s_lshl_b32 s2, s46, 3
	s_add_u32 s2, s20, s2
	s_addc_u32 s23, s21, 0
	s_add_u32 s22, s2, 0x3e0
	s_addc_u32 s23, s23, 0
	v_mov_b64_e32 v[24:25], s[22:23]
	v_mov_b32_e32 v21, 0
	s_and_saveexec_b64 s[24:25], s[100:101]
	v_lshl_add_u64 v[26:27], v[20:21], 2, s[20:21]
	global_load_dword v28, v[26:27], off
	global_load_dword v29, v[24:25], off
	global_load_dword v30, v[26:27], off offset:4
	global_load_dword v31, v[24:25], off offset:4
	s_or_b64 exec, exec, s[24:25]
	v_mbcnt_lo_u32_b32 v1, -1, 0
	v_mbcnt_hi_u32_b32 v1, -1, v1
	v_and_b32_e32 v12, 64, v1
	v_xor_b32_e32 v13, 1, v1
	v_add_u32_e32 v12, 64, v12
	v_xor_b32_e32 v14, 2, v1
	v_cmp_lt_i32_e32 vcc, v13, v12
	v_xor_b32_e32 v15, 4, v1
	v_xor_b32_e32 v16, 8, v1
	v_cndmask_b32_e32 v13, v1, v13, vcc
	v_cmp_lt_i32_e32 vcc, v14, v12
	v_xor_b32_e32 v17, 16, v1
	v_xor_b32_e32 v18, 32, v1
	v_cndmask_b32_e32 v14, v1, v14, vcc
	v_cmp_lt_i32_e32 vcc, v15, v12
	v_lshlrev_b32_e32 v205, 2, v14
	s_mov_b32 s0, 0x4138aa3b
	v_cndmask_b32_e32 v15, v1, v15, vcc
	v_cmp_lt_i32_e32 vcc, v16, v12
	v_lshlrev_b32_e32 v210, 2, v15
	s_mov_b32 s1, 0x4038aa3b
	v_cndmask_b32_e32 v16, v1, v16, vcc
	v_cmp_lt_i32_e32 vcc, v17, v12
	v_lshlrev_b32_e32 v211, 2, v16
	s_waitcnt vmcnt(0)
	v_and_b32_e32 v14, 0x7fffffff, v2
	v_cndmask_b32_e32 v17, v1, v17, vcc
	v_cmp_lt_i32_e32 vcc, v18, v12
	v_max_f32_e64 v4, |v4|, |v4|
	v_max_f32_e64 v5, |v5|, |v5|
	v_cndmask_b32_e32 v12, v1, v18, vcc
	v_lshlrev_b32_e32 v1, 2, v13
	v_and_b32_e32 v15, 0x7fffffff, v3
	v_mul_f32_e32 v16, v7, v6
	v_max_f32_e32 v4, v5, v4
	v_lshlrev_b32_e32 v13, 2, v17
	v_mul_f32_e32 v17, v8, v9
	ds_bpermute_b32 v5, v1, v14
	ds_bpermute_b32 v14, v1, v15
	ds_bpermute_b32 v15, v1, v16
	v_max3_f32 v4, |v11|, |v10|, v4
	ds_bpermute_b32 v16, v1, v17
	ds_bpermute_b32 v10, v1, v4
	v_max_f32_e64 v2, |v2|, |v2|
	v_max_f32_e64 v3, |v3|, |v3|
	s_waitcnt lgkmcnt(4)
; __global__ void __launch_bounds__(NWAVES * 64, 2) mega_fwd(Args args) {
;     ...
;             float gq = fabsf(P.q_norm_g[F.lane]), gk = fabsf(P.k_norm_g[F.lane]), gb = fmaxf(fmaxf(fabsf(P.rel_bias[F.lane]), fabsf(P.rel_bias[64 + F.lane])), fmaxf(fabsf(P.rel_bias[128 + F.lane]), fabsf(P.rel_bias[192 + F.lane])));
;             gq = wave_max(gq); gk = wave_max(gk); gb = wave_max(gb);
;             const float bound = 64.f * C2 * gq * gk + 2.f * LOG2E * gb, shift = bound > 100.f ? bound : 0.f;
;             dattn::Outs OU{(const bf16*)(P.ws + WS_SG), (bf16*)(P.ws + WS_BR), P.subln_g, compute_lam(P, F.lane)};
;     ...
;             S.wcyc = 0ull;
;     ...
;             {
;                 if (F.tid == 0) *(float*)(al + dattn::L_MISC) = shift;
;                 for (int e = F.tid; e < 1024; e += NWAVES * 64) { const int c = e >> 9, jj = e & 511, d = jj - dattn::TAB_OFF;
;                     const int dd = d > 113 ? 113 : d;
;                     ((float*)(al + dattn::L_TAB))[e] = d < 0 ? -__builtin_inff() : (P.rel_bias[(t5_bucket(dd) * NH + cur.h) * 2 + c] - P.rel_bias[(31 * NH + cur.h) * 2 + c]) * LOG2E - shift; }
;                 __syncthreads();
	v_max_f32_e32 v5, v5, v5
	s_waitcnt lgkmcnt(3)
	v_max_f32_e32 v11, v14, v14
	s_waitcnt lgkmcnt(2)
	v_fmac_f32_e32 v15, v7, v6
	s_waitcnt lgkmcnt(1)
	v_fmac_f32_e32 v16, v8, v9
	v_max_f32_e32 v2, v2, v5
	v_max_f32_e32 v3, v3, v11
	ds_bpermute_b32 v5, v205, v15
	s_waitcnt lgkmcnt(1)
	v_max_f32_e32 v9, v10, v10
	ds_bpermute_b32 v6, v205, v16
	ds_bpermute_b32 v7, v205, v2
	ds_bpermute_b32 v8, v205, v3
	v_max_f32_e32 v4, v4, v9
	ds_bpermute_b32 v9, v205, v4
	s_waitcnt lgkmcnt(4)
	v_add_f32_e32 v5, v15, v5
	s_waitcnt lgkmcnt(3)
	v_add_f32_e32 v6, v16, v6
	s_waitcnt lgkmcnt(2)
	v_max_f32_e32 v7, v7, v7
	s_waitcnt lgkmcnt(1)
	v_max_f32_e32 v8, v8, v8
	ds_bpermute_b32 v10, v210, v5
	ds_bpermute_b32 v11, v210, v6
	v_max_f32_e32 v2, v2, v7
	v_max_f32_e32 v3, v3, v8
	s_waitcnt lgkmcnt(2)
	v_max_f32_e32 v9, v9, v9
	ds_bpermute_b32 v7, v210, v2
	ds_bpermute_b32 v8, v210, v3
	v_max_f32_e32 v4, v4, v9
	ds_bpermute_b32 v9, v210, v4
	s_waitcnt lgkmcnt(4)
	v_add_f32_e32 v5, v5, v10
	s_waitcnt lgkmcnt(3)
	v_add_f32_e32 v6, v6, v11
	ds_bpermute_b32 v10, v211, v5
	ds_bpermute_b32 v11, v211, v6
	s_waitcnt lgkmcnt(4)
	v_max_f32_e32 v7, v7, v7
	s_waitcnt lgkmcnt(3)
	v_max_f32_e32 v8, v8, v8
	v_max_f32_e32 v2, v2, v7
	v_max_f32_e32 v3, v3, v8
	s_waitcnt lgkmcnt(2)
	v_max_f32_e32 v9, v9, v9
	ds_bpermute_b32 v7, v211, v2
	ds_bpermute_b32 v8, v211, v3
	v_max_f32_e32 v4, v4, v9
	ds_bpermute_b32 v9, v211, v4
	s_waitcnt lgkmcnt(4)
	v_add_f32_e32 v5, v5, v10
	s_waitcnt lgkmcnt(3)
	v_add_f32_e32 v10, v6, v11
	ds_bpermute_b32 v6, v13, v5
	s_waitcnt lgkmcnt(3)
	v_max_f32_e32 v7, v7, v7
	s_waitcnt lgkmcnt(2)
	v_max_f32_e32 v8, v8, v8
	v_max_f32_e32 v2, v2, v7
	v_max_f32_e32 v3, v3, v8
	s_waitcnt lgkmcnt(1)
	v_max_f32_e32 v7, v9, v9
	ds_bpermute_b32 v11, v13, v10
	ds_bpermute_b32 v15, v13, v3
	v_max_f32_e32 v4, v4, v7
	ds_bpermute_b32 v14, v13, v2
	s_waitcnt lgkmcnt(3)
	v_add_f32_e32 v6, v5, v6
	ds_bpermute_b32 v5, v13, v4
	s_waitcnt lgkmcnt(3)
	v_add_f32_e32 v7, v10, v11
	s_waitcnt lgkmcnt(2)
	v_max_f32_e32 v10, v15, v15
	v_lshlrev_b32_e32 v12, 2, v12
	s_waitcnt lgkmcnt(1)
	v_max_f32_e32 v9, v14, v14
	v_max_f32_e32 v3, v3, v10
	s_waitcnt lgkmcnt(0)
	v_max_f32_e32 v5, v5, v5
	v_max_f32_e32 v2, v2, v9
	ds_bpermute_b32 v10, v12, v3
	v_max_f32_e32 v4, v4, v5
	ds_bpermute_b32 v9, v12, v2
	ds_bpermute_b32 v5, v12, v4
	ds_bpermute_b32 v8, v12, v6
	s_waitcnt lgkmcnt(3)
	v_max_f32_e32 v10, v10, v10
	v_max_f32_e32 v10, v3, v10
	s_waitcnt lgkmcnt(2)
	v_max_f32_e32 v9, v9, v9
	s_waitcnt lgkmcnt(1)
	v_max_f32_e32 v3, v5, v5
	v_max_f32_e32 v2, v2, v9
	v_max_f32_e32 v3, v4, v3
	ds_bpermute_b32 v9, v12, v7
	v_pk_mul_f32 v[2:3], v[2:3], s[0:1]
	s_mov_b32 s0, 0x42c80000
	v_fmac_f32_e32 v3, v2, v10
	v_cmp_lt_f32_e32 vcc, s0, v3
	s_nop 1
	v_cndmask_b32_e32 v10, 0, v3, vcc
	s_and_saveexec_b64 s[0:1], s[12:13]
	s_add_i32 s2, 0, 0x23800
	v_mov_b32_e32 v2, s2
	ds_write_b32 v2, v10
	s_or_b64 exec, exec, s[0:1]
	v_lshl_add_u32 v3, v0, 2, 0
	v_add_u32_e32 v12, 0x12800, v3
	s_mov_b64 s[22:23], 0
	v_sub_f32_e32 v28, v28, v29
	v_sub_f32_e32 v30, v30, v31
	v_fma_f32 v28, v28, s26, -v10
	v_fma_f32 v30, v30, s26, -v10
	v_mov_b32_e32 v13, 0xff800000
	v_cndmask_b32_e64 v28, v13, v28, s[100:101]
	v_cndmask_b32_e64 v30, v13, v30, s[100:101]
	ds_write_b32 v12, v28
	ds_write_b32 v12, v30 offset:2048
